# lever 2 prologue de-serialisation: GLA pre-pass loads the next unit's low-rank rows before the unit's final stores (counted vmcnt instead of a full drain at unit start)
# speedup vs baseline: 1.0016x; 1.0016x over previous
.LBB0_609:
	s_lshl_b32 s0, s36, 3
	s_and_b32 s38, s0, 0xffffffc0
	s_and_saveexec_b64 s[62:63], s[2:3]
	s_cbranch_execz .LBB0_611
	s_cmp_lg_u32 s36, s30
	s_cbranch_scc1 .Lgl_lrpf_use
	s_ashr_i32 s39, s38, 31
	s_lshl_b64 s[64:65], s[38:39], 6
	v_lshl_add_u64 v[18:19], v[52:53], 0, s[64:65]
	global_load_dwordx4 v[18:21], v[18:19], off
	s_waitcnt vmcnt(0)
	ds_write_b128 v72, v[18:21]
	s_branch .LBB0_611
.Lgl_lrpf_use:
	s_waitcnt vmcnt(9)
	ds_write_b128 v72, v[120:123]

.LBB0_613:
	s_or_b64 exec, exec, s[64:65]
	s_waitcnt lgkmcnt(0)
	s_barrier
	s_add_i32 s98, s36, s68
	s_min_u32 s98, s98, 0x7ff
	s_lshl_b32 s98, s98, 3
	s_and_b32 s98, s98, 0xffffffc0
	s_mov_b32 s99, 0
	s_lshl_b64 s[100:101], s[98:99], 6
	s_and_saveexec_b64 s[98:99], s[2:3]
	s_cbranch_execz .Lgl_lrpf_skip
	v_lshl_add_u64 v[124:125], v[52:53], 0, s[100:101]
	global_load_dwordx4 v[120:123], v[124:125], off
.Lgl_lrpf_skip:
	s_or_b64 exec, exec, s[98:99]
	s_and_saveexec_b64 s[64:65], s[6:7]
	s_cbranch_execz .LBB0_618
	s_mov_b64 s[66:67], 0
	v_mov_b32_e32 v18, v70
	v_mov_b32_e32 v19, v50
